# FFT steps D/F/H: the four halo loads per iteration no longer each wait vmcnt(0) in their own exec-masked block (all six loads issued together, one wait); stacked on P8 + attention edits
# baseline (speedup 1.0000x reference)
.LBB0_434:
	v_add_u32_e32 v16, s23, v26
	v_ashrrev_i32_e32 v17, 31, v16
	v_lshl_add_u64 v[2:3], v[16:17], 1, s[86:87]
	v_lshl_add_u64 v[32:33], v[16:17], 1, s[88:89]
	global_load_dwordx4 v[6:9], v[2:3], off
	v_cmp_lt_i32_e32 vcc, 0, v16
	v_mov_b32_e32 v29, 0
	v_mov_b32_e32 v30, 0
	v_mov_b32_e32 v17, 0
	v_mov_b32_e32 v31, 0
	v_cmp_gt_i32_e64 s[6:7], s5, v16
	s_and_saveexec_b64 s[92:93], vcc
	global_load_ushort v30, v[2:3], off offset:-2
	global_load_ushort v31, v[32:33], off offset:-2
	s_mov_b64 exec, s[92:93]
	s_nop 0
	s_and_saveexec_b64 s[92:93], s[6:7]
	global_load_ushort v29, v[2:3], off offset:16
	global_load_ushort v17, v[32:33], off offset:16
	s_mov_b64 exec, s[92:93]
	s_nop 0
	global_load_dwordx4 v[2:5], v[32:33], off
	s_waitcnt vmcnt(1)
	v_lshlrev_b32_e32 v30, 16, v30
	v_lshlrev_b32_e32 v29, 16, v29
	v_lshlrev_b32_e32 v31, 16, v31
	v_lshlrev_b32_e32 v17, 16, v17
	s_branch .LBB0_433

.LBB0_446:
	v_add_u32_e32 v14, s23, v29
	v_ashrrev_i32_e32 v15, 31, v14
	v_lshl_add_u64 v[2:3], v[14:15], 1, s[84:85]
	v_lshl_add_u64 v[16:17], v[14:15], 1, s[86:87]
	global_load_dwordx4 v[6:9], v[2:3], off
	v_cmp_lt_i32_e32 vcc, 0, v14
	v_mov_b32_e32 v30, 0
	v_mov_b32_e32 v32, 0
	v_mov_b32_e32 v15, 0
	v_mov_b32_e32 v31, 0
	v_cmp_gt_i32_e64 s[6:7], s5, v14
	s_and_saveexec_b64 s[90:91], vcc
	global_load_ushort v32, v[2:3], off offset:-2
	global_load_ushort v31, v[16:17], off offset:-2
	s_mov_b64 exec, s[90:91]
	s_nop 0
	s_and_saveexec_b64 s[90:91], s[6:7]
	global_load_ushort v30, v[2:3], off offset:16
	global_load_ushort v15, v[16:17], off offset:16
	s_mov_b64 exec, s[90:91]
	s_nop 0
	global_load_dwordx4 v[2:5], v[16:17], off
	s_waitcnt vmcnt(1)
	v_lshlrev_b32_e32 v32, 16, v32
	v_lshlrev_b32_e32 v30, 16, v30
	v_lshlrev_b32_e32 v31, 16, v31
	v_lshlrev_b32_e32 v15, 16, v15
	s_branch .LBB0_445

.LBB0_458:
	v_add_u32_e32 v14, s6, v30
	v_ashrrev_i32_e32 v15, 31, v14
	v_lshl_add_u64 v[2:3], v[14:15], 1, s[76:77]
	v_lshl_add_u64 v[28:29], v[14:15], 1, s[80:81]
	global_load_dwordx4 v[6:9], v[2:3], off
	v_cmp_lt_i32_e32 vcc, 0, v14
	v_mov_b32_e32 v16, 0
	v_mov_b32_e32 v32, 0
	v_mov_b32_e32 v17, 0
	v_mov_b32_e32 v31, 0
	v_cmp_gt_i32_e64 s[6:7], s5, v14
	s_and_saveexec_b64 s[86:87], vcc
	global_load_ushort v32, v[2:3], off offset:-2
	global_load_ushort v31, v[28:29], off offset:-2
	s_mov_b64 exec, s[86:87]
	s_nop 0
	s_and_saveexec_b64 s[86:87], s[6:7]
	global_load_ushort v16, v[2:3], off offset:16
	global_load_ushort v17, v[28:29], off offset:16
	s_mov_b64 exec, s[86:87]
	s_nop 0
	global_load_dwordx4 v[2:5], v[28:29], off
	s_waitcnt vmcnt(1)
	v_lshlrev_b32_e32 v32, 16, v32
	v_lshlrev_b32_e32 v16, 16, v16
	v_lshlrev_b32_e32 v31, 16, v31
	v_lshlrev_b32_e32 v17, 16, v17
	s_branch .LBB0_457
